# GEMM phases: one static s_setprio 1 for waves 4-7 (wr==1) at the stagger barrier, per-phase flips removed, reset to 0 at phase end
# speedup vs baseline: 1.0067x; 1.0018x over previous
; __host__ __device__ inline bool phase_empty(int ph) { if (ph == 0) return false; const int L = (ph - 1) / 9, k = (ph - 1) % 9; if (k == 5) return true; if (k == 8) return L != 3; return (L % 2 == 0) && (k == 2 || k == 3); }
; __global__ void __launch_bounds__(512) mega_fwd(Args a) {
;     ...
;     for (int ph = a.ph_lo; ph < a.ph_hi; ++ph) {
;         if (phase_empty(ph)) continue;
.LBB0_10:
	s_setprio 0
	s_add_i32 s90, s90, 1
	s_cmp_ge_i32 s90, s91
	s_cbranch_scc1 .LBB0_829

; __device__ __forceinline__ int opq_tid() { int t = threadIdx.x; asm volatile("" : "+v"(t)); return t; }
;     __device__ __forceinline__ void prefetch(const Unit& u, PG8_LAS unsigned char* slot, int tid, int wid) const { if (f.on) xslot_fetch(f.st + 8 * (u.pm * BM), f.c1 + u.pn * BM, f.c2 + u.pn * BM, slot, tid, wid); }
;     __device__ __forceinline__ void prefetch(const Unit& u, PG8_LAS unsigned char* slot, int tid, int wid) const { xslot_fetch(f.st + 8 * (u.pm * BM), f.c1 + u.pn * BM, f.c2 + u.pn * BM, slot, tid, wid); }
; template <class Epi, class Sched, bool ALIGN_EPI = false, bool SP2 = false>
; __device__ __forceinline__ void gemm_phase(PG8_LAS unsigned char* lds, const Gemm g, const Sched& S, const Epi& E) {
;     const int tid = opq_tid(), wid = __builtin_amdgcn_readfirstlane(tid >> 6), lane = tid & 63, wr = wid >> 2, wc = wid & 3, fr = lane & 15, fq = lane >> 4;
;     const int K = g.K, nt = K / BK;
;     unsigned voffA[2], voffB[2];
; #pragma unroll
;     for (int i = 0; i < 2; ++i) { int R, C; stage_rc(tid * 16 + i * 8192, R, C); const int Rb = Epi::PERM ? ((R & ~31) + perm32(R & 31)) : R;
;         voffA[i] = (unsigned)(R * K + C) * 2u; voffB[i] = (unsigned)(Rb * K + C) * 2u; }
;     const size_t kstep = (size_t)(BK * 2);
;     const size_t hstep = (size_t)HALF * K * 2;
;     const size_t tstep = 2 * hstep;
;     const unsigned ldsw = (unsigned)wid * 1024u;
;     const int aoff = lds_byte(wr * 64 + fr, fq * 8), boff = lds_byte(wc * 32 + fr, fq * 8);
;     ...
;     Unit cur, nxt; int ui = 0;
;     if (!S.next(0, cur)) return;
;     f32x4 acc[2][2][4][2];
; #pragma unroll
;     for (int a = 0; a < 2; ++a)
; #pragma unroll
;         for (int b = 0; b < 2; ++b)
; #pragma unroll
;             for (int m = 0; m < 4; ++m)
; #pragma unroll
;                 for (int n = 0; n < 2; ++n) acc[a][b][m][n] = (f32x4){0.f, 0.f, 0.f, 0.f};
;     bf16x8 At[4][2], B0[2][2], B1[2][2];
;     typename Epi::Pre pre;
;     const char* cA = (const char*)g.A + (size_t)cur.pm * tstep; const char* cB = (const char*)g.Bt + (size_t)cur.pn * tstep;
;     S.a_ready(cur);
;     E.prefetch(cur, lds + XSLOT_OFF, tid, wid);
;     if constexpr (SP2) {
;         PG8_STAGE(PG8_SB(0, 0), cB, voffB); PG8_STAGE(PG8_SB(0, 1), cB + hstep, voffB); PG8_STAGE(PG8_SA(0, 0), cA, voffA); PG8_STAGE(PG8_SA(0, 1), cA + hstep, voffA);
;         if (wr == 1) PG8_BAR;
.LBB0_51:
	v_bfe_i32 v3, v4, 27, 1
	v_lshlrev_b32_e32 v1, 4, v4
	v_lshrrev_b32_e32 v3, 22, v3
	v_add_u32_e32 v3, v1, v3
	v_and_b32_e32 v3, 0xfffffc00, v3
	v_sub_u32_e32 v3, v1, v3
	v_lshrrev_b32_e32 v8, 4, v3
	v_lshrrev_b32_e32 v0, 26, v5
	v_bitop3_b32 v8, v8, v3, 32 bitop3:0x6c
	v_ashrrev_i32_e32 v3, 31, v3
	v_add_u32_e32 v0, v4, v0
	v_lshrrev_b32_e32 v3, 26, v3
	v_ashrrev_i32_e32 v0, 6, v0
	v_add_u32_e32 v3, v8, v3
	v_lshlrev_b32_e32 v9, 3, v0
	v_ashrrev_i32_e32 v10, 6, v3
	v_lshlrev_b32_e32 v0, 5, v0
	v_and_b32_e32 v3, 32, v0
	v_mul_i32_i24_e32 v0, 64, v10
	v_and_b32_e32 v9, -16, v9
	v_sub_u32_e32 v0, v8, v0
	v_mov_b32_e32 v12, 1
	v_add_u32_e32 v9, v10, v9
	v_ashrrev_i16_sdwa v0, v12, sext(v0) dst_sel:DWORD dst_unused:UNUSED_PAD src0_sel:DWORD src1_sel:BYTE_0
	v_bfe_i32 v20, v0, 0, 16
	v_lshlrev_b32_e32 v0, 1, v9
	v_lshrrev_b32_e32 v11, 2, v9
	v_and_b32_e32 v10, 3, v10
	s_mov_b32 s4, 0x7fffffe0
	v_and_b32_e32 v0, 24, v0
	v_and_b32_e32 v11, 4, v11
	v_and_or_b32 v10, v9, s4, v10
	v_or3_b32 v10, v10, v11, v0
	v_add_u32_e32 v8, v3, v20
	v_mul_lo_u32 v21, v9, s26
	v_mul_lo_u32 v9, v10, s26
	v_add_u32_e32 v1, 0x2000, v1
	v_add_lshl_u32 v0, v8, v21, 1
	v_add_lshl_u32 v172, v9, v8, 1
	v_ashrrev_i32_e32 v8, 31, v1
	v_lshrrev_b32_e32 v8, 22, v8
	v_add_u32_e32 v8, v1, v8
	v_ashrrev_i32_e32 v8, 10, v8
	v_mul_i32_i24_e32 v9, 0x400, v8
	v_sub_u32_e32 v1, v1, v9
	v_lshrrev_b32_e32 v9, 4, v1
	v_bitop3_b32 v1, v9, v1, 32 bitop3:0x6c
	v_ashrrev_i32_e32 v10, 31, v1
	s_lshl_b32 s61, s26, 9
	v_lshrrev_b32_e32 v10, 26, v10
	s_lshl_b32 s8, s26, 8
	s_mul_i32 s15, s61, s23
	v_readlane_b32 s24, v250, 6
	v_lshlrev_b32_e32 v9, 3, v8
	v_add_u32_e32 v10, v1, v10
	s_mul_hi_i32 s14, s61, s23
	v_readlane_b32 s25, v250, 7
	s_add_u32 s46, s24, s15
	v_and_b32_e32 v9, -16, v9
	v_ashrrev_i32_e32 v11, 6, v10
	v_lshlrev_b32_e32 v8, 5, v8
	s_addc_u32 s47, s25, s14
	s_mul_i32 s15, s61, s22
	v_add_u32_e32 v9, v11, v9
	v_and_b32_e32 v22, 32, v8
	v_and_b32_e32 v8, 0xc0, v10
	s_mul_hi_i32 s14, s61, s22
	s_add_u32 s48, s16, s15
	v_sub_u32_e32 v1, v1, v8
	v_lshlrev_b32_e32 v8, 1, v9
	v_lshrrev_b32_e32 v10, 2, v9
	v_and_b32_e32 v11, 3, v11
	s_addc_u32 s49, s17, s14
	v_ashrrev_i16_sdwa v1, v12, sext(v1) dst_sel:DWORD dst_unused:UNUSED_PAD src0_sel:DWORD src1_sel:BYTE_0
	v_and_b32_e32 v8, 24, v8
	v_and_b32_e32 v10, 4, v10
	v_and_or_b32 v11, v9, s4, v11
	s_add_i32 s62, s60, 0
	v_bfe_i32 v23, v1, 0, 16
	v_or3_b32 v8, v11, v10, v8
	s_add_i32 m0, s62, 0x10000
	v_add_u32_e32 v1, v22, v23
	v_mul_lo_u32 v8, v8, s26
	s_ashr_i32 s27, s30, 8
	global_load_lds_dwordx4 v172, s[48:49]
	s_add_i32 m0, s62, 0x12000
	v_add_lshl_u32 v176, v8, v1, 1
	s_add_u32 s24, s48, s8
	global_load_lds_dwordx4 v176, s[48:49]
	s_addc_u32 s25, s49, 0
	s_add_i32 m0, s62, 0x14000
	v_mov_b32_e32 v173, v2
	v_mov_b32_e32 v177, v2
	global_load_lds_dwordx4 v172, s[24:25]
	s_add_i32 m0, s62, 0x16000
	s_add_i32 s63, s62, 0x2000
	v_mul_lo_u32 v24, v9, s26
	v_lshl_add_u64 v[12:13], s[24:25], 0, v[172:173]
	v_lshl_add_u64 v[14:15], s[24:25], 0, v[176:177]
	global_load_lds_dwordx4 v176, s[24:25]
	s_mov_b32 m0, s62
	s_add_u32 s24, s46, s8
	v_add_lshl_u32 v174, v1, v24, 1
	global_load_lds_dwordx4 v0, s[46:47]
	s_mov_b32 m0, s63
	s_addc_u32 s25, s47, 0
	s_add_i32 s64, s62, 0x4000
	global_load_lds_dwordx4 v174, s[46:47]
	s_mov_b32 m0, s64
	s_add_i32 s65, s62, 0x6000
	global_load_lds_dwordx4 v0, s[24:25]
	s_mov_b32 m0, s65
	v_writelane_b32 v253, s68, 12
	global_load_lds_dwordx4 v174, s[24:25]
	s_nop 0
	v_writelane_b32 v253, s69, 13
	v_writelane_b32 v253, s70, 14
	v_writelane_b32 v253, s71, 15
	v_writelane_b32 v253, s72, 16
	v_writelane_b32 v253, s73, 17
	v_writelane_b32 v254, s76, 41
	v_writelane_b32 v253, s74, 18
	v_mov_b32_e32 v1, v2
	v_mov_b32_e32 v175, v2
	s_cmp_eq_u32 s27, 1
	v_writelane_b32 v254, s77, 42
	v_writelane_b32 v253, s75, 19
	v_lshl_add_u64 v[8:9], s[48:49], 0, v[172:173]
	v_lshl_add_u64 v[10:11], s[48:49], 0, v[176:177]
	v_lshl_add_u64 v[16:17], s[46:47], 0, v[0:1]
	v_lshl_add_u64 v[18:19], s[46:47], 0, v[174:175]
	s_cselect_b64 s[24:25], -1, 0
	s_cmp_lg_u32 s27, 1
	s_cbranch_scc1 .LBB0_53
	s_setprio 1
	s_barrier

; __device__ __forceinline__ int opq_tid() { int t = threadIdx.x; asm volatile("" : "+v"(t)); return t; }
;     __device__ __forceinline__ void prefetch(const Unit& u, PG8_LAS unsigned char* slot, int tid, int wid) const { if (f.on) xslot_fetch(f.st + 8 * (u.pm * BM), f.c1 + u.pn * BM, f.c2 + u.pn * BM, slot, tid, wid); }
;     __device__ __forceinline__ void prefetch(const Unit& u, PG8_LAS unsigned char* slot, int tid, int wid) const { xslot_fetch(f.st + 8 * (u.pm * BM), f.c1 + u.pn * BM, f.c2 + u.pn * BM, slot, tid, wid); }
; template <class Epi, class Sched, bool ALIGN_EPI = false, bool SP2 = false>
; __device__ __forceinline__ void gemm_phase(PG8_LAS unsigned char* lds, const Gemm g, const Sched& S, const Epi& E) {
;     const int tid = opq_tid(), wid = __builtin_amdgcn_readfirstlane(tid >> 6), lane = tid & 63, wr = wid >> 2, wc = wid & 3, fr = lane & 15, fq = lane >> 4;
;     const int K = g.K, nt = K / BK;
;     unsigned voffA[2], voffB[2];
; #pragma unroll
;     for (int i = 0; i < 2; ++i) { int R, C; stage_rc(tid * 16 + i * 8192, R, C); const int Rb = Epi::PERM ? ((R & ~31) + perm32(R & 31)) : R;
;         voffA[i] = (unsigned)(R * K + C) * 2u; voffB[i] = (unsigned)(Rb * K + C) * 2u; }
;     const size_t kstep = (size_t)(BK * 2);
;     const size_t hstep = (size_t)HALF * K * 2;
;     const size_t tstep = 2 * hstep;
;     const unsigned ldsw = (unsigned)wid * 1024u;
;     const int aoff = lds_byte(wr * 64 + fr, fq * 8), boff = lds_byte(wc * 32 + fr, fq * 8);
;     ...
;     Unit cur, nxt; int ui = 0;
;     if (!S.next(0, cur)) return;
;     f32x4 acc[2][2][4][2];
; #pragma unroll
;     for (int a = 0; a < 2; ++a)
; #pragma unroll
;         for (int b = 0; b < 2; ++b)
; #pragma unroll
;             for (int m = 0; m < 4; ++m)
; #pragma unroll
;                 for (int n = 0; n < 2; ++n) acc[a][b][m][n] = (f32x4){0.f, 0.f, 0.f, 0.f};
;     bf16x8 At[4][2], B0[2][2], B1[2][2];
;     typename Epi::Pre pre;
;     const char* cA = (const char*)g.A + (size_t)cur.pm * tstep; const char* cB = (const char*)g.Bt + (size_t)cur.pn * tstep;
;     S.a_ready(cur);
;     E.prefetch(cur, lds + XSLOT_OFF, tid, wid);
;     if constexpr (SP2) {
;         PG8_STAGE(PG8_SB(0, 0), cB, voffB); PG8_STAGE(PG8_SB(0, 1), cB + hstep, voffB); PG8_STAGE(PG8_SA(0, 0), cA, voffA); PG8_STAGE(PG8_SA(0, 1), cA + hstep, voffA);
;         if (wr == 1) PG8_BAR;
.LBB0_445:
	v_mov_b32_e32 v4, v220
	s_cmpk_gt_i32 s8, 0xaff
	v_readfirstlane_b32 s4, v4
	s_cbranch_scc1 .LBB0_463
	v_lshlrev_b32_e32 v1, 4, v4
	v_add_u32_e32 v0, 0x2000, v1
	v_ashrrev_i32_e32 v3, 31, v0
	v_lshrrev_b32_e32 v3, 22, v3
	v_add_u32_e32 v3, v0, v3
	v_ashrrev_i32_e32 v18, 10, v3
	s_lshl_b64 s[2:3], s[2:3], 2
	v_readlane_b32 s14, v250, 22
	v_mul_i32_i24_e32 v3, 0x400, v18
	v_readlane_b32 s15, v250, 23
	s_add_u32 s2, s14, s2
	v_sub_u32_e32 v0, v0, v3
	s_addc_u32 s3, s15, s3
	s_ashr_i32 s5, s4, 6
	v_lshrrev_b32_e32 v3, 4, v0
	s_ashr_i32 s16, s4, 8
	s_lshl_b32 s13, s5, 10
	s_lshl_b64 s[0:1], s[0:1], 2
	v_readlane_b32 s14, v250, 20
	v_bitop3_b32 v0, v3, v0, 32 bitop3:0x6c
	v_readlane_b32 s15, v250, 21
	s_add_u32 s14, s14, s0
	v_ashrrev_i32_e32 v3, 31, v0
	s_addc_u32 s15, s15, s1
	v_readlane_b32 s0, v253, 2
	v_lshrrev_b32_e32 v3, 26, v3
	v_readlane_b32 s1, v253, 3
	s_mov_b32 s18, s0
	v_add_u32_e32 v3, v0, v3
	s_waitcnt lgkmcnt(0)
	v_lshlrev_b32_e32 v5, 3, v18
	s_mul_i32 s1, s18, 0xb00000
	v_readlane_b32 s17, v250, 36
	v_ashrrev_i32_e32 v19, 6, v3
	v_and_b32_e32 v5, -16, v5
	s_mul_hi_i32 s0, s0, 0xb00000
	s_add_u32 s28, s17, s1
	v_readlane_b32 s1, v250, 37
	v_add_u32_e32 v5, v19, v5
	s_addc_u32 s29, s1, s0
	v_and_b32_e32 v6, 3, v19
	s_mov_b32 s0, 0x1fffe0
	v_lshrrev_b32_e32 v7, 2, v5
	v_lshlrev_b32_e32 v8, 1, v5
	v_and_b32_e32 v3, 0xc0, v3
	v_and_or_b32 v6, v5, s0, v6
	v_and_b32_e32 v7, 4, v7
	v_and_b32_e32 v8, 24, v8
	v_sub_u32_e32 v0, v0, v3
	v_mov_b32_e32 v9, 1
	v_or3_b32 v6, v6, v7, v8
	v_lshlrev_b32_e32 v7, 5, v18
	v_ashrrev_i16_sdwa v0, v9, sext(v0) dst_sel:DWORD dst_unused:UNUSED_PAD src0_sel:DWORD src1_sel:BYTE_0
	v_and_b32_e32 v7, 32, v7
	v_bfe_i32 v20, v0, 0, 16
	v_add_lshl_u32 v3, v7, v20, 1
	v_lshl_add_u32 v0, v6, 11, v3
	v_lshl_add_u32 v164, v5, 11, v3
	v_bfe_i32 v3, v4, 27, 1
	v_lshrrev_b32_e32 v3, 22, v3
	v_add_u32_e32 v3, v1, v3
	v_and_b32_e32 v3, 0xfffffc00, v3
	v_sub_u32_e32 v1, v1, v3
	v_lshrrev_b32_e32 v3, 4, v1
	v_bitop3_b32 v3, v3, v1, 32 bitop3:0x6c
	v_ashrrev_i32_e32 v1, 31, v1
	v_lshrrev_b32_e32 v1, 26, v1
	v_add_u32_e32 v1, v3, v1
	v_ashrrev_i32_e32 v5, 31, v4
	v_ashrrev_i32_e32 v21, 6, v1
	v_lshrrev_b32_e32 v1, 26, v5
	v_add_u32_e32 v1, v4, v1
	v_ashrrev_i32_e32 v22, 6, v1
	v_lshlrev_b32_e32 v1, 3, v22
	v_and_b32_e32 v1, -16, v1
	v_add_u32_e32 v1, v21, v1
	v_and_b32_e32 v6, 3, v21
	s_ashr_i32 s30, s8, 31
	v_and_or_b32 v6, v1, s0, v6
	s_lshr_b32 s0, s30, 29
	s_add_i32 s0, s8, s0
	s_ashr_i32 s1, s0, 3
	s_and_b32 s0, s0, -8
	s_sub_i32 s0, s8, s0
	s_cmp_lt_i32 s0, 0
	s_movk_i32 s17, 0x161
	s_cselect_b32 s17, s17, 0x160
	s_mul_i32 s0, s0, s17
	s_add_i32 s0, s0, s1
	s_mul_hi_i32 s1, s0, 0x2e8ba2e9
	s_lshr_b32 s17, s1, 31
	s_ashr_i32 s1, s1, 5
	s_add_i32 s1, s1, s17
	s_lshl_b32 s17, s1, 3
	s_mulk_i32 s1, 0xb0
	s_sub_i32 s1, s0, s1
	s_bfe_u32 s0, s1, 0x3001c
	s_add_i32 s18, s1, s0
	s_sext_i32_i16 s19, s18
	s_and_b32 s18, s18, 0xfff8
	s_sub_i32 s1, s1, s18
	s_sext_i32_i16 s1, s1
	s_lshr_b32 s0, s19, 3
	s_add_i32 s22, s17, s1
	s_ashr_i32 s23, s22, 31
	s_bfe_i64 s[0:1], s[0:1], 0x100000
	s_ashr_i32 s44, s19, 3
	s_lshl_b64 s[18:19], s[22:23], 19
	s_lshl_b64 s[0:1], s[0:1], 19
	s_mov_b32 s56, s24
	s_add_u32 s24, s28, s0
	s_addc_u32 s25, s29, s1
	s_lshl_b32 s0, s22, 11
	s_ashr_i32 s1, s0, 31
	v_lshrrev_b32_e32 v7, 2, v1
	v_lshlrev_b32_e32 v8, 1, v1
	s_lshl_b64 s[0:1], s[0:1], 2
	v_readlane_b32 s20, v250, 18
	v_and_b32_e32 v7, 4, v7
	v_and_b32_e32 v8, 24, v8
	v_readlane_b32 s21, v250, 19
	s_add_u32 s0, s20, s0
	v_or3_b32 v6, v6, v7, v8
	v_mul_i32_i24_e32 v8, 64, v21
	s_addc_u32 s1, s21, s1
	s_lshl_b32 s20, s44, 8
	v_sub_u32_e32 v3, v3, v8
	s_ashr_i32 s21, s20, 31
	v_lshlrev_b32_e32 v7, 5, v22
	v_ashrrev_i16_sdwa v3, v9, sext(v3) dst_sel:DWORD dst_unused:UNUSED_PAD src0_sel:DWORD src1_sel:BYTE_0
	s_lshl_b64 s[20:21], s[20:21], 2
	v_and_b32_e32 v7, 32, v7
	v_bfe_i32 v23, v3, 0, 16
	s_add_u32 s26, s14, s20
	v_add_lshl_u32 v3, v7, v23, 1
	s_addc_u32 s27, s15, s21
	v_lshl_add_u32 v166, v6, 11, v3
	s_add_u32 s20, s2, s20
	v_lshlrev_b32_e32 v6, 2, v4
	s_addc_u32 s21, s3, s21
	v_ashrrev_i32_e32 v7, 31, v6
	s_add_i32 s23, s13, 0
	v_lshl_add_u64 v[8:9], v[6:7], 2, s[0:1]
	s_add_i32 m0, s23, 0x20000
	s_cmp_lt_i32 s5, 4
	global_load_lds_dwordx4 v[8:9], off
	v_lshlrev_b64 v[8:9], 2, v[4:5]
	s_movk_i32 s0, 0xfc00
	v_lshl_add_u64 v[12:13], s[20:21], 0, v[8:9]
	s_mov_b32 s1, -1
	s_cselect_b64 s[38:39], -1, 0
	s_lshl_b32 s31, s5, 8
	v_lshl_add_u64 v[10:11], s[26:27], 0, v[8:9]
	v_lshl_add_u64 v[12:13], v[12:13], 0, s[0:1]
	s_add_i32 s0, s31, 0
	v_cndmask_b32_e64 v11, v13, v11, s[38:39]
	v_cndmask_b32_e64 v10, v12, v10, s[38:39]
	s_add_i32 m0, s0, 0x22000
	v_lshl_add_u32 v168, v1, 11, v3
	global_load_lds_dword v[10:11], off
	s_add_i32 m0, s23, 0x10000
	v_mov_b32_e32 v167, v2
	global_load_lds_dwordx4 v166, s[24:25]
	s_add_i32 m0, s23, 0x12000
	s_add_u32 s0, s24, 0x40000
	global_load_lds_dwordx4 v0, s[24:25]
	s_addc_u32 s1, s25, 0
	s_add_i32 m0, s23, 0x14000
	v_mov_b32_e32 v1, v2
	global_load_lds_dwordx4 v166, s[0:1]
	s_add_i32 m0, s23, 0x16000
	v_mov_b32_e32 v169, v2
	global_load_lds_dwordx4 v0, s[0:1]
	v_readlane_b32 s0, v250, 4
	v_readlane_b32 s1, v250, 5
	s_add_u32 s26, s0, s18
	s_addc_u32 s27, s1, s19
	s_add_i32 s34, s23, 0x2000
	s_mov_b32 m0, s23
	s_add_u32 s0, s26, 0x40000
	global_load_lds_dwordx4 v168, s[26:27]
	s_mov_b32 m0, s34
	s_addc_u32 s1, s27, 0
	s_add_i32 s35, s23, 0x4000
	global_load_lds_dwordx4 v164, s[26:27]
	s_mov_b32 m0, s35
	s_add_i32 s36, s23, 0x6000
	global_load_lds_dwordx4 v168, s[0:1]
	s_mov_b32 m0, s36
	v_mov_b32_e32 v165, v2
	global_load_lds_dwordx4 v164, s[0:1]
	s_cmp_eq_u32 s16, 1
	v_mov_b32_e32 v242, 0x358637bd
	v_lshl_add_u64 v[16:17], s[24:25], 0, v[166:167]
	s_waitcnt lgkmcnt(0)
	v_lshl_add_u64 v[14:15], s[24:25], 0, v[0:1]
	v_lshl_add_u64 v[10:11], s[26:27], 0, v[168:169]
	s_cselect_b64 s[0:1], -1, 0
	s_cmp_lg_u32 s16, 1
	v_lshl_add_u64 v[12:13], s[26:27], 0, v[164:165]
	s_cbranch_scc1 .LBB0_448
	s_setprio 1
	s_barrier

;     __device__ __forceinline__ void prefetch(const Unit& u, PG8_LAS unsigned char* slot, int tid, int wid) const { if (f.on) xslot_fetch(f.st + 8 * (u.pm * BM), f.c1 + u.pn * BM, f.c2 + u.pn * BM, slot, tid, wid); }
;     __device__ __forceinline__ void prefetch(const Unit& u, PG8_LAS unsigned char* slot, int tid, int wid) const { xslot_fetch(f.st + 8 * (u.pm * BM), f.c1 + u.pn * BM, f.c2 + u.pn * BM, slot, tid, wid); }
;     __device__ __forceinline__ void prefetch(const Unit& u, PG8_LAS unsigned char* slot, int tid, int wid) const { if (st_prev) xslot_fetch(st_prev + 8 * (u.pm * BM), gp + u.pn * BM, bp + u.pn * BM, slot, tid, wid); }
; #define PG8_BAR __builtin_amdgcn_s_barrier()
; template <class Epi, class Sched, bool ALIGN_EPI = false, bool SP2 = false>
; __device__ __forceinline__ void gemm_phase(PG8_LAS unsigned char* lds, const Gemm g, const Sched& S, const Epi& E) {
;     ...
;     for (int i = 0; i < 2; ++i) { int R, C; stage_rc(tid * 16 + i * 8192, R, C); const int Rb = Epi::PERM ? ((R & ~31) + perm32(R & 31)) : R;
;         voffA[i] = (unsigned)(R * K + C) * 2u; voffB[i] = (unsigned)(Rb * K + C) * 2u; }
;     const size_t kstep = (size_t)(BK * 2);
;     const size_t hstep = (size_t)HALF * K * 2;
;     const size_t tstep = 2 * hstep;
;     const unsigned ldsw = (unsigned)wid * 1024u;
;     const int aoff = lds_byte(wr * 64 + fr, fq * 8), boff = lds_byte(wc * 32 + fr, fq * 8);
;     ...
;     Unit cur, nxt; int ui = 0;
;     if (!S.next(0, cur)) return;
;     f32x4 acc[2][2][4][2];
; #pragma unroll
;     for (int a = 0; a < 2; ++a)
; #pragma unroll
;         for (int b = 0; b < 2; ++b)
; #pragma unroll
;             for (int m = 0; m < 4; ++m)
; #pragma unroll
;                 for (int n = 0; n < 2; ++n) acc[a][b][m][n] = (f32x4){0.f, 0.f, 0.f, 0.f};
;     bf16x8 At[4][2], B0[2][2], B1[2][2];
;     typename Epi::Pre pre;
;     const char* cA = (const char*)g.A + (size_t)cur.pm * tstep; const char* cB = (const char*)g.Bt + (size_t)cur.pn * tstep;
;     S.a_ready(cur);
;     E.prefetch(cur, lds + XSLOT_OFF, tid, wid);
;     if constexpr (SP2) {
;         PG8_STAGE(PG8_SB(0, 0), cB, voffB); PG8_STAGE(PG8_SB(0, 1), cB + hstep, voffB); PG8_STAGE(PG8_SA(0, 0), cA, voffA); PG8_STAGE(PG8_SA(0, 1), cA + hstep, voffA);
;         if (wr == 1) PG8_BAR;
.LBB0_504:
	v_lshrrev_b32_e32 v0, 26, v5
	v_add_u32_e32 v0, v4, v0
	v_ashrrev_i32_e32 v16, 6, v0
	v_bfe_i32 v0, v4, 27, 1
	v_lshlrev_b32_e32 v1, 4, v4
	v_lshrrev_b32_e32 v0, 22, v0
	v_add_u32_e32 v0, v1, v0
	v_and_b32_e32 v0, 0xfffffc00, v0
	v_sub_u32_e32 v0, v1, v0
	v_lshrrev_b32_e32 v3, 4, v0
	v_bitop3_b32 v3, v3, v0, 32 bitop3:0x6c
	v_ashrrev_i32_e32 v0, 31, v0
	v_lshrrev_b32_e32 v0, 26, v0
	s_ashr_i32 s29, s28, 31
	v_add_u32_e32 v0, v3, v0
	s_lshl_b64 s[2:3], s[28:29], 19
	v_readlane_b32 s16, v250, 4
	v_ashrrev_i32_e32 v17, 6, v0
	v_readlane_b32 s17, v250, 5
	s_add_u32 s2, s16, s2
	s_sext_i32_i16 s16, s55
	v_lshlrev_b32_e32 v8, 3, v16
	v_mul_i32_i24_e32 v9, 64, v17
	s_addc_u32 s3, s17, s3
	s_ashr_i32 s17, s16, 31
	v_and_b32_e32 v8, -16, v8
	v_sub_u32_e32 v3, v3, v9
	v_mov_b32_e32 v11, 1
	s_lshl_b64 s[16:17], s[16:17], 19
	v_add_u32_e32 v0, v17, v8
	v_ashrrev_i16_sdwa v3, v11, sext(v3) dst_sel:DWORD dst_unused:UNUSED_PAD src0_sel:DWORD src1_sel:BYTE_0
	s_add_u32 s30, s4, s16
	v_lshlrev_b32_e32 v8, 5, v16
	v_bfe_i32 v18, v3, 0, 16
	v_lshlrev_b32_e32 v3, 1, v0
	v_lshrrev_b32_e32 v9, 2, v0
	v_and_b32_e32 v10, 3, v17
	s_mov_b32 s16, 0x1fffe0
	v_and_b32_e32 v8, 32, v8
	v_and_b32_e32 v3, 24, v3
	v_and_b32_e32 v9, 4, v9
	v_and_or_b32 v10, v0, s16, v10
	v_or3_b32 v3, v10, v9, v3
	v_add_lshl_u32 v8, v8, v18, 1
	v_add_u32_e32 v1, 0x2000, v1
	v_lshl_add_u32 v164, v3, 11, v8
	v_ashrrev_i32_e32 v3, 31, v1
	v_lshrrev_b32_e32 v3, 22, v3
	v_add_u32_e32 v3, v1, v3
	v_ashrrev_i32_e32 v19, 10, v3
	v_mul_i32_i24_e32 v3, 0x400, v19
	v_sub_u32_e32 v1, v1, v3
	v_lshrrev_b32_e32 v3, 4, v1
	v_bitop3_b32 v1, v3, v1, 32 bitop3:0x6c
	v_lshl_add_u32 v0, v0, 11, v8
	v_ashrrev_i32_e32 v8, 31, v1
	v_lshrrev_b32_e32 v8, 26, v8
	v_add_u32_e32 v8, v1, v8
	v_lshlrev_b32_e32 v3, 3, v19
	v_ashrrev_i32_e32 v20, 6, v8
	v_and_b32_e32 v8, 0xc0, v8
	v_and_b32_e32 v3, -16, v3
	v_sub_u32_e32 v1, v1, v8
	v_add_u32_e32 v3, v20, v3
	v_ashrrev_i16_sdwa v1, v11, sext(v1) dst_sel:DWORD dst_unused:UNUSED_PAD src0_sel:DWORD src1_sel:BYTE_0
	s_addc_u32 s31, s5, s17
	v_lshlrev_b32_e32 v9, 5, v19
	v_bfe_i32 v21, v1, 0, 16
	v_lshlrev_b32_e32 v1, 1, v3
	v_lshrrev_b32_e32 v8, 2, v3
	v_and_b32_e32 v10, 3, v20
	s_add_i32 s29, s37, 0
	v_and_b32_e32 v9, 32, v9
	v_and_b32_e32 v1, 24, v1
	v_and_b32_e32 v8, 4, v8
	v_and_or_b32 v10, v3, s16, v10
	s_add_i32 m0, s29, 0x10000
	s_ashr_i32 s24, s18, 8
	v_or3_b32 v1, v10, v8, v1
	v_add_lshl_u32 v8, v9, v21, 1
	global_load_lds_dwordx4 v164, s[30:31]
	s_add_i32 m0, s29, 0x12000
	v_lshl_add_u32 v168, v1, 11, v8
	s_add_u32 s16, s30, 0x40000
	global_load_lds_dwordx4 v168, s[30:31]
	s_addc_u32 s17, s31, 0
	s_add_i32 m0, s29, 0x14000
	s_add_i32 s48, s29, 0x2000
	global_load_lds_dwordx4 v164, s[16:17]
	s_add_i32 m0, s29, 0x16000
	v_lshl_add_u32 v166, v3, 11, v8
	global_load_lds_dwordx4 v168, s[16:17]
	s_mov_b32 m0, s29
	s_add_u32 s16, s2, 0x40000
	global_load_lds_dwordx4 v0, s[2:3]
	s_mov_b32 m0, s48
	s_addc_u32 s17, s3, 0
	s_add_i32 s49, s29, 0x4000
	global_load_lds_dwordx4 v166, s[2:3]
	s_mov_b32 m0, s49
	s_add_i32 s50, s29, 0x6000
	global_load_lds_dwordx4 v0, s[16:17]
	s_mov_b32 m0, s50
	v_mov_b32_e32 v165, v2
	global_load_lds_dwordx4 v166, s[16:17]
	v_mov_b32_e32 v169, v2
	v_mov_b32_e32 v1, v2
	v_mov_b32_e32 v167, v2
	s_cmp_eq_u32 s24, 1
	v_mov_b32_e32 v218, 0x358637bd
	s_waitcnt lgkmcnt(0)
	v_lshl_add_u64 v[14:15], s[30:31], 0, v[164:165]
	v_lshl_add_u64 v[12:13], s[30:31], 0, v[168:169]
	v_lshl_add_u64 v[8:9], s[2:3], 0, v[0:1]
	s_cselect_b64 s[16:17], -1, 0
	s_cmp_lg_u32 s24, 1
	v_lshl_add_u64 v[10:11], s[2:3], 0, v[166:167]
	s_cbranch_scc1 .LBB0_506
	s_setprio 1
	s_barrier
